# s5_ktab (S5 copy): per-(n,dir) factor computed once by 128 lanes and shared through LDS instead of 16x redundantly in 4 serialized passes
# speedup vs baseline: 1.0105x; 1.0010x over previous
; __device__ void s5_ktab(int swave, const Params& p, int j, char* shm, int bidx, int nblk) {
;     ...
;   for (int unit = bidx; unit < 16 * 127; unit += nblk) {
;     const int g = unit / 127, delta = unit % 127;
;     const int tau = delta >= 63 ? delta - 63 : 63 - delta;
;     __syncthreads();
;     for (int e = tid; e < 2 * 64 * 16; e += 512) {
;       const int pp = e & 15, n = (e >> 4) & 63, dir = e >> 10;
;       const float lr = fminf(lam_re[(dir * 16 + g) * 64 + n], -1e-4f), li = lam_im[(dir * 16 + g) * 64 + n];
;       const float dt = __expf(log_dt[dir * 16 + g]);
;       float c1, s1; cis_d((double)li * (double)dt, c1, s1);
;       const float m1 = __expf(lr * dt);
;       const float ar = m1 * c1, ai = m1 * s1;
;       const float den = lr * lr + li * li, nr = ar - 1.f;
;       const float cr = (nr * lr + ai * li) / den, ci = (ai * lr - nr * li) / den;
;       float ce, se; cis_d((double)li * (double)dt * (double)tau, ce, se);
;       const float me = __expf(lr * dt * (float)tau);
;       const float pr = me * ce, pi = me * se;
;       const float wr_ = pr * cr - pi * ci, wi_ = pr * ci + pi * cr;
;       const float br = b_re[(g * 64 + n) * 16 + pp], bi = b_im[(g * 64 + n) * 16 + pp];
;       wre[e] = wr_ * br - wi_ * bi; wim[e] = wr_ * bi + wi_ * br;
;     }
.LBB0_484:
	v_cmp_gt_u32_e32 vcc, 0x80, v16
	s_and_saveexec_b64 s[34:35], vcc
	s_cbranch_execz .Lkt_p1_done
	v_lshrrev_b32_e32 v10, 6, v16
	v_and_b32_e32 v21, 63, v16
	v_lshl_add_u32 v10, v10, 4, s40
	v_lshl_or_b32 v12, v10, 6, v21
	v_ashrrev_i32_e32 v13, 31, v12
	v_lshlrev_b64 v[12:13], 2, v[12:13]
	v_lshl_add_u64 v[14:15], s[10:11], 0, v[12:13]
	v_lshl_add_u64 v[12:13], s[12:13], 0, v[12:13]
	v_ashrrev_i32_e32 v11, 31, v10
	v_lshl_add_u64 v[22:23], v[10:11], 2, s[14:15]
	global_load_dword v11, v[14:15], off
	global_load_dword v15, v[12:13], off
	global_load_dword v10, v[22:23], off
	s_waitcnt vmcnt(0)
	v_max_f32_e32 v11, v11, v11
	v_min_f32_e32 v14, 0xb8d1b717, v11
	v_mul_f32_e32 v24, v15, v15
	v_fmac_f32_e32 v24, v14, v14
	v_mul_f32_e32 v10, 0x3fb8aa3b, v10
	v_exp_f32_e32 v22, v10
	v_cvt_f64_f32_e32 v[10:11], v15
	v_cvt_f64_f32_e32 v[12:13], v22
	v_mul_f64 v[10:11], v[10:11], v[12:13]
	v_mul_f64 v[12:13], v[10:11], s[90:91]
	v_rndne_f64_e32 v[12:13], v[12:13]
	v_fma_f64 v[12:13], s[92:93], v[12:13], v[10:11]
	v_cvt_f32_f64_e32 v12, v[12:13]
	v_mul_f32_e32 v22, v14, v22
	v_mul_f32_e32 v12, 0.15915494, v12
	v_mul_f32_e32 v23, 0x3fb8aa3b, v22
	v_cos_f32_e32 v13, v12
	v_exp_f32_e32 v23, v23
	v_sin_f32_e32 v12, v12
	v_mul_f64 v[10:11], v[10:11], v[4:5]
	v_fma_f32 v13, v23, v13, -1.0
	v_mul_f32_e32 v12, v23, v12
	v_mul_f32_e32 v23, v14, v13
	v_fmac_f32_e32 v23, v15, v12
	v_div_scale_f32 v25, s[20:21], v24, v24, v23
	v_rcp_f32_e32 v26, v25
	v_mul_f32_e32 v13, v15, v13
	v_fma_f32 v12, v14, v12, -v13
	v_div_scale_f32 v13, s[20:21], v24, v24, v12
	v_fma_f32 v27, -v25, v26, 1.0
	v_fmac_f32_e32 v26, v27, v26
	v_div_scale_f32 v27, vcc, v23, v24, v23
	v_rcp_f32_e32 v14, v13
	v_mul_f32_e32 v28, v27, v26
	v_fma_f32 v29, -v25, v28, v27
	v_fmac_f32_e32 v28, v29, v26
	v_fma_f32 v25, -v25, v28, v27
	v_fma_f32 v15, -v13, v14, 1.0
	v_div_fmas_f32 v25, v25, v26, v28
	v_fmac_f32_e32 v14, v15, v14
	v_div_scale_f32 v15, vcc, v12, v24, v12
	v_div_fixup_f32 v23, v25, v24, v23
	v_mul_f32_e32 v25, v15, v14
	v_fma_f32 v26, -v13, v25, v15
	v_fmac_f32_e32 v25, v26, v14
	v_fma_f32 v13, -v13, v25, v15
	v_div_fmas_f32 v13, v13, v14, v25
	v_div_fixup_f32 v14, v13, v24, v12
	v_mul_f64 v[12:13], v[10:11], s[90:91]
	v_rndne_f64_e32 v[12:13], v[12:13]
	v_fmac_f64_e32 v[10:11], s[92:93], v[12:13]
	v_cvt_f32_f64_e32 v10, v[10:11]
	v_mul_f32_e32 v12, v22, v6
	v_mul_f32_e32 v10, 0.15915494, v10
	v_mul_f32_e32 v12, 0x3fb8aa3b, v12
	v_cos_f32_e32 v11, v10
	v_sin_f32_e32 v10, v10
	v_exp_f32_e32 v12, v12
	s_nop 0
	v_mul_f32_e32 v10, v12, v10
	v_mul_f32_e32 v11, v12, v11
	v_mul_f32_e32 v12, v10, v14
	v_mul_f32_e32 v22, v10, v23
	v_fma_f32 v15, v11, v23, -v12
	v_fmac_f32_e32 v22, v11, v14
	v_lshlrev_b32_e32 v8, 3, v16
	v_add_u32_e32 v8, 0x4000, v8
	ds_write2_b32 v8, v15, v22 offset1:1
.Lkt_p1_done:
	s_or_b64 exec, exec, s[34:35]
	s_waitcnt lgkmcnt(0)
	s_barrier
	v_lshlrev_b32_e32 v10, 6, v17
	v_lshl_add_u32 v10, v7, 2, v10
	v_mov_b32_e32 v11, 0
	v_lshlrev_b32_e32 v9, 3, v17
	v_lshl_add_u64 v[12:13], s[16:17], 0, v[10:11]
	v_lshl_add_u64 v[14:15], s[18:19], 0, v[10:11]
	v_add_u32_e32 v9, 0x4000, v9
	global_load_dword v21, v[12:13], off
	global_load_dword v22, v[14:15], off
	global_load_dword v23, v[12:13], off offset:2048
	global_load_dword v29, v[14:15], off offset:2048
	ds_read_b64 v[24:25], v9
	ds_read_b64 v[26:27], v9 offset:256
	ds_read_b64 v[12:13], v9 offset:512
	ds_read_b64 v[14:15], v9 offset:768
	s_waitcnt vmcnt(0) lgkmcnt(0)
	v_mul_f32_e32 v10, v22, v25
	v_mul_f32_e32 v11, v21, v25
	v_fma_f32 v10, v21, v24, -v10
	v_fmac_f32_e32 v11, v22, v24
	ds_write2st64_b32 v20, v10, v11 offset1:32
	v_mul_f32_e32 v28, v29, v27
	v_mul_f32_e32 v9, v23, v27
	v_fma_f32 v28, v23, v26, -v28
	v_fmac_f32_e32 v9, v29, v26
	ds_write2st64_b32 v20, v28, v9 offset0:8 offset1:40
	v_mul_f32_e32 v10, v22, v13
	v_mul_f32_e32 v11, v21, v13
	v_fma_f32 v10, v21, v12, -v10
	v_fmac_f32_e32 v11, v22, v12
	ds_write2st64_b32 v20, v10, v11 offset0:16 offset1:48
	v_mul_f32_e32 v28, v29, v15
	v_mul_f32_e32 v9, v23, v15
	v_fma_f32 v28, v23, v14, -v28
	v_fmac_f32_e32 v9, v29, v14
	ds_write2st64_b32 v20, v28, v9 offset0:24 offset1:56
